# v27 + SWA inner loop issues the 4 K loads before the 4 V loads with counted vmcnt waits
# speedup vs baseline: 1.0086x; 1.0086x over previous
.LBB0_255:
	v_add_u32_e32 v36, v89, v69
	v_mov_b32_e32 v94, v32
	v_mad_i64_i32 v[36:37], s[0:1], v36, s55, v[82:83]
	v_lshlrev_b64 v[124:125], 1, v[64:65]
	v_lshl_add_u64 v[36:37], v[36:37], 0, v[76:77]
	v_add_u32_e32 v126, 16, v64
	v_mov_b32_e32 v127, v65
	v_add_co_u32_e64 v32, s[0:1], s33, v36
	v_lshl_add_u64 v[120:121], v[36:37], 0, s[42:43]
	s_nop 0
	v_addc_co_u32_e64 v33, s[0:1], 0, v37, s[0:1]
	global_load_dwordx4 v[32:35], v[32:33], off
	s_nop 0
	global_load_dwordx4 v[112:115], v[120:121], off offset:32
	global_load_dwordx4 v[116:119], v[120:121], off offset:96
	v_lshl_add_u64 v[38:39], v[84:85], 0, v[124:125]
	v_lshl_add_u64 v[38:39], v[38:39], 0, v[164:165]
	global_load_dwordx4 v[120:123], v[120:121], off offset:64
	v_lshl_add_u64 v[124:125], v[86:87], 0, v[124:125]
	v_lshl_add_u64 v[124:125], v[124:125], 0, v[164:165]
	v_lshl_add_u64 v[126:127], v[126:127], 1, v[86:87]
	v_lshl_add_u64 v[126:127], v[126:127], 0, v[164:165]
	global_load_dwordx4 v[96:99], v[38:39], off
	global_load_dwordx4 v[100:103], v[38:39], off offset:32
	global_load_dwordx4 v[104:107], v[124:125], off
	global_load_dwordx4 v[108:111], v[126:127], off
	v_add_u32_e32 v40, v89, v75
	v_add_u32_e32 v154, s56, v40
	v_add_u32_e32 v154, -1, v154
	v_lshl_add_u32 v156, s56, 1, -1
	v_subrev_u32_e32 v149, 0, v154
	v_subrev_u32_e32 v150, 1, v154
	v_subrev_u32_e32 v151, 2, v154
	v_add_u32_e32 v71, 1, v71
	v_cmp_ge_u32_e32 vcc, v71, v73
	v_subrev_u32_e32 v95, 3, v154
	s_or_b64 s[50:51], vcc, s[50:51]
	v_cmp_gt_u32_e32 vcc, v156, v150
	v_cmp_gt_u32_e64 s[2:3], v156, v95
	v_cmp_gt_u32_e64 s[28:29], v156, v149
	v_cmp_gt_u32_e64 s[0:1], v156, v151
	v_subrev_u32_e32 v124, 16, v154
	v_cmp_gt_u32_e64 s[12:13], v156, v124
	v_subrev_u32_e32 v75, 32, v75
	v_add_u32_e32 v64, 32, v64
	v_add_u32_e32 v69, 32, v69
	s_waitcnt vmcnt(7)
	v_mfma_f32_32x32x16_bf16 v[32:47], v[32:35], v[48:51], 0
	s_waitcnt vmcnt(6)
	v_mfma_f32_32x32x16_bf16 v[32:47], v[112:115], v[52:55], v[32:47]
	v_subrev_u32_e32 v112, 8, v154
	v_cmp_gt_u32_e64 s[4:5], v156, v112
	v_subrev_u32_e32 v113, 9, v154
	v_subrev_u32_e32 v114, 10, v154
	v_subrev_u32_e32 v115, 11, v154
	v_cmp_gt_u32_e64 s[6:7], v156, v113
	v_cmp_gt_u32_e64 s[8:9], v156, v114
	s_waitcnt vmcnt(4)
	v_mfma_f32_32x32x16_bf16 v[32:47], v[120:123], v[56:59], v[32:47]
	v_subrev_u32_e32 v125, 17, v154
	v_cmp_gt_u32_e64 s[10:11], v156, v115
	v_subrev_u32_e32 v120, 18, v154
	v_subrev_u32_e32 v121, 19, v154
	v_cmp_gt_u32_e64 s[14:15], v156, v125
	v_subrev_u32_e32 v122, 24, v154
	v_subrev_u32_e32 v123, 25, v154
	v_mfma_f32_32x32x16_bf16 v[32:47], v[116:119], v[60:63], v[32:47]
	v_cmp_gt_u32_e64 s[16:17], v156, v120
	v_cmp_gt_u32_e64 s[18:19], v156, v121
	v_subrev_u32_e32 v126, 26, v154
	v_subrev_u32_e32 v127, 27, v154
	v_cmp_gt_u32_e64 s[20:21], v156, v122
	v_cmp_gt_u32_e64 s[22:23], v156, v123
	v_cmp_gt_u32_e64 s[24:25], v156, v126
	s_nop 4
	v_max_f32_e32 v95, v32, v32
	v_cndmask_b32_e32 v112, v93, v33, vcc
	v_max_f32_e32 v95, 0xf149f2ca, v95
	v_max_f32_e32 v112, v112, v112
	v_cndmask_b32_e64 v95, v93, v95, s[28:29]
	v_cndmask_b32_e64 v113, v93, v34, s[0:1]
	v_cndmask_b32_e64 v114, v93, v35, s[2:3]
	v_max_f32_e32 v95, v95, v112
	v_cndmask_b32_e64 v115, v93, v36, s[4:5]
	v_cndmask_b32_e64 v116, v93, v37, s[6:7]
	v_max3_f32 v95, v95, v113, v114
	v_cndmask_b32_e64 v117, v93, v38, s[8:9]
	v_cndmask_b32_e64 v118, v93, v39, s[10:11]
	v_max3_f32 v95, v95, v115, v116
	v_cndmask_b32_e64 v119, v93, v40, s[12:13]
	v_cndmask_b32_e64 v120, v93, v41, s[14:15]
	v_max3_f32 v95, v95, v117, v118
	v_cndmask_b32_e64 v121, v93, v42, s[16:17]
	v_cndmask_b32_e64 v122, v93, v43, s[18:19]
	v_max3_f32 v95, v95, v119, v120
	v_cmp_gt_u32_e64 s[26:27], v156, v127
	v_cndmask_b32_e64 v123, v93, v44, s[20:21]
	v_cndmask_b32_e64 v124, v93, v45, s[22:23]
	v_max3_f32 v95, v95, v121, v122
	v_cndmask_b32_e64 v125, v93, v46, s[24:25]
	v_cndmask_b32_e64 v126, v93, v47, s[26:27]
	v_max3_f32 v95, v95, v123, v124
	v_max3_f32 v95, v95, v125, v126
	v_mov_b32_e32 v112, v95
	s_nop 1
	v_permlane32_swap_b32_e32 v95, v112
	v_max3_f32 v95, v81, v95, v112
	v_sub_f32_e32 v32, v32, v95
	v_sub_f32_e32 v33, v33, v95
	v_sub_f32_e32 v34, v34, v95
	v_sub_f32_e32 v35, v35, v95
	v_sub_f32_e32 v36, v36, v95
	v_sub_f32_e32 v37, v37, v95
	v_sub_f32_e32 v38, v38, v95
	v_sub_f32_e32 v39, v39, v95
	v_sub_f32_e32 v112, v81, v95
	v_mul_f32_e32 v32, 0x3fb8aa3b, v32
	v_mul_f32_e32 v33, 0x3fb8aa3b, v33
	v_mul_f32_e32 v34, 0x3fb8aa3b, v34
	v_mul_f32_e32 v35, 0x3fb8aa3b, v35
	v_mul_f32_e32 v36, 0x3fb8aa3b, v36
	v_mul_f32_e32 v37, 0x3fb8aa3b, v37
	v_mul_f32_e32 v38, 0x3fb8aa3b, v38
	v_mul_f32_e32 v39, 0x3fb8aa3b, v39
	v_sub_f32_e32 v40, v40, v95
	v_sub_f32_e32 v41, v41, v95
	v_sub_f32_e32 v42, v42, v95
	v_sub_f32_e32 v43, v43, v95
	v_sub_f32_e32 v44, v44, v95
	v_sub_f32_e32 v45, v45, v95
	v_sub_f32_e32 v46, v46, v95
	v_sub_f32_e32 v47, v47, v95
	v_mov_b32_e32 v81, v95
	v_mul_f32_e32 v95, 0x3fb8aa3b, v112
	v_exp_f32_e32 v32, v32
	v_exp_f32_e32 v33, v33
	v_exp_f32_e32 v34, v34
	v_exp_f32_e32 v35, v35
	v_exp_f32_e32 v112, v36
	v_exp_f32_e32 v37, v37
	v_exp_f32_e32 v38, v38
	v_exp_f32_e32 v39, v39
	v_exp_f32_e32 v36, v95
	v_cndmask_b32_e64 v95, 0, v32, s[28:29]
	v_cndmask_b32_e32 v113, 0, v33, vcc
	v_cndmask_b32_e64 v114, 0, v34, s[0:1]
	v_cndmask_b32_e64 v115, 0, v35, s[2:3]
	v_cndmask_b32_e64 v112, 0, v112, s[4:5]
	v_cndmask_b32_e64 v37, 0, v37, s[6:7]
	v_cndmask_b32_e64 v38, 0, v38, s[8:9]
	v_cndmask_b32_e64 v39, 0, v39, s[10:11]
	v_pk_mul_f32 v[14:15], v[14:15], v[36:37] op_sel_hi:[1,0]
	v_pk_mul_f32 v[12:13], v[12:13], v[36:37] op_sel_hi:[1,0]
	v_pk_mul_f32 v[10:11], v[10:11], v[36:37] op_sel_hi:[1,0]
	v_pk_mul_f32 v[8:9], v[8:9], v[36:37] op_sel_hi:[1,0]
	v_pk_mul_f32 v[6:7], v[6:7], v[36:37] op_sel_hi:[1,0]
	v_pk_mul_f32 v[4:5], v[4:5], v[36:37] op_sel_hi:[1,0]
	v_pk_mul_f32 v[2:3], v[2:3], v[36:37] op_sel_hi:[1,0]
	v_pk_mul_f32 v[0:1], v[0:1], v[36:37] op_sel_hi:[1,0]
	v_pk_mul_f32 v[30:31], v[30:31], v[36:37] op_sel_hi:[1,0]
	v_cvt_pk_bf16_f32 v32, v95, v113
	v_cvt_pk_bf16_f32 v33, v114, v115
	v_cvt_pk_bf16_f32 v34, v112, v37
	v_cvt_pk_bf16_f32 v35, v38, v39
	v_pk_mul_f32 v[28:29], v[28:29], v[36:37] op_sel_hi:[1,0]
	v_pk_mul_f32 v[26:27], v[26:27], v[36:37] op_sel_hi:[1,0]
	v_pk_mul_f32 v[24:25], v[24:25], v[36:37] op_sel_hi:[1,0]
	v_pk_mul_f32 v[22:23], v[22:23], v[36:37] op_sel_hi:[1,0]
	v_pk_mul_f32 v[20:21], v[20:21], v[36:37] op_sel_hi:[1,0]
	v_pk_mul_f32 v[18:19], v[18:19], v[36:37] op_sel_hi:[1,0]
	v_pk_mul_f32 v[16:17], v[16:17], v[36:37] op_sel_hi:[1,0]
	v_add_f32_e32 v95, 0, v95
	s_waitcnt vmcnt(3)
	v_permlane32_swap_b32_e32 v96, v98
	v_permlane32_swap_b32_e32 v97, v99
	s_nop 1
	v_mfma_f32_32x32x16_bf16 v[0:15], v[96:99], v[32:35], v[0:15]
	v_add_f32_e32 v95, v113, v95
	v_mul_f32_e32 v40, 0x3fb8aa3b, v40
	v_mul_f32_e32 v41, 0x3fb8aa3b, v41
	v_mul_f32_e32 v42, 0x3fb8aa3b, v42
	v_mul_f32_e32 v43, 0x3fb8aa3b, v43
	v_mul_f32_e32 v44, 0x3fb8aa3b, v44
	v_mul_f32_e32 v45, 0x3fb8aa3b, v45
	s_waitcnt vmcnt(1)
	v_permlane32_swap_b32_e32 v104, v106
	v_permlane32_swap_b32_e32 v105, v107
	s_nop 1
	v_mfma_f32_32x32x16_bf16 v[16:31], v[104:107], v[32:35], v[16:31]
	v_mul_f32_e32 v46, 0x3fb8aa3b, v46
	v_mul_f32_e32 v47, 0x3fb8aa3b, v47
	v_add_f32_e32 v95, v114, v95
	v_exp_f32_e32 v40, v40
	v_exp_f32_e32 v41, v41
	v_exp_f32_e32 v42, v42
	v_exp_f32_e32 v43, v43
	v_exp_f32_e32 v44, v44
	v_exp_f32_e32 v45, v45
	v_exp_f32_e32 v46, v46
	v_exp_f32_e32 v47, v47
	v_add_f32_e32 v95, v115, v95
	v_add_f32_e32 v95, v112, v95
	v_add_f32_e32 v37, v37, v95
	v_add_f32_e32 v37, v38, v37
	v_cndmask_b32_e64 v40, 0, v40, s[12:13]
	v_cndmask_b32_e64 v41, 0, v41, s[14:15]
	v_cndmask_b32_e64 v42, 0, v42, s[16:17]
	v_cndmask_b32_e64 v43, 0, v43, s[18:19]
	v_cndmask_b32_e64 v44, 0, v44, s[20:21]
	v_cndmask_b32_e64 v45, 0, v45, s[22:23]
	v_cndmask_b32_e64 v46, 0, v46, s[24:25]
	v_cndmask_b32_e64 v47, 0, v47, s[26:27]
	v_add_f32_e32 v37, v39, v37
	v_cvt_pk_bf16_f32 v32, v40, v41
	v_cvt_pk_bf16_f32 v33, v42, v43
	v_cvt_pk_bf16_f32 v34, v44, v45
	v_cvt_pk_bf16_f32 v35, v46, v47
	v_add_f32_e32 v37, v40, v37
	v_add_f32_e32 v37, v41, v37
	v_permlane32_swap_b32_e32 v100, v102
	v_permlane32_swap_b32_e32 v101, v103
	s_nop 1
	v_mfma_f32_32x32x16_bf16 v[0:15], v[100:103], v[32:35], v[0:15]
	s_waitcnt vmcnt(0)
	v_permlane32_swap_b32_e32 v108, v110
	v_permlane32_swap_b32_e32 v109, v111
	s_nop 1
	v_mfma_f32_32x32x16_bf16 v[16:31], v[108:111], v[32:35], v[16:31]
	v_add_f32_e32 v32, v42, v37
	v_add_f32_e32 v32, v43, v32
	v_add_f32_e32 v32, v44, v32
	v_add_f32_e32 v32, v45, v32
	v_add_f32_e32 v32, v46, v32
	v_add_f32_e32 v32, v47, v32
	v_fmac_f32_e32 v32, v94, v36
	s_andn2_b64 exec, exec, s[50:51]
	s_cbranch_execnz .LBB0_255
	s_or_b64 exec, exec, s[50:51]
	s_branch .LBB0_252
